# GEMM unit prologues: accumulator zero-fill done by 7 zero-operand 32x32x16 MFMAs + 16 v_mov instead of 128 v_mov (matrix core is idle there)
# speedup vs baseline: 1.0049x; 1.0049x over previous
.LBB0_124:
	v_mov_b32_e32 v2, 0
	v_mov_b32_e32 v3, 0
	v_mov_b32_e32 v4, 0
	v_mov_b32_e32 v5, 0
	v_mov_b32_e32 v6, 0
	v_mov_b32_e32 v7, 0
	v_mov_b32_e32 v8, 0
	v_mov_b32_e32 v9, 0
	v_mov_b32_e32 v10, 0
	v_mov_b32_e32 v11, 0
	v_mov_b32_e32 v12, 0
	v_mov_b32_e32 v13, 0
	v_mov_b32_e32 v14, 0
	v_mov_b32_e32 v15, 0
	v_mov_b32_e32 v16, 0
	v_mov_b32_e32 v17, 0
	v_mfma_f32_32x32x16_bf16 v[18:33], v[2:5], v[2:5], 0
	v_mfma_f32_32x32x16_bf16 v[34:49], v[2:5], v[2:5], 0
	v_mfma_f32_32x32x16_bf16 v[50:65], v[2:5], v[2:5], 0
	v_mfma_f32_32x32x16_bf16 v[66:81], v[2:5], v[2:5], 0
	v_mfma_f32_32x32x16_bf16 v[82:97], v[2:5], v[2:5], 0
	v_mfma_f32_32x32x16_bf16 v[98:113], v[2:5], v[2:5], 0
	v_mfma_f32_32x32x16_bf16 v[114:129], v[2:5], v[2:5], 0
	s_andn2_b64 vcc, exec, s[14:15]
	s_waitcnt vmcnt(0)
	s_nop 15
	s_nop 3
	s_cbranch_vccnz .LBB0_127
	s_add_u32 s20, s20, 0x80
	s_addc_u32 s21, s21, 0
	s_add_u32 s43, s22, 0x100
	s_addc_u32 s44, s23, 0
	s_mov_b32 s22, 0
	s_mov_b64 s[50:51], 0x80

.LBB0_426:
	v_mov_b32_e32 v2, 0
	v_mov_b32_e32 v3, 0
	v_mov_b32_e32 v4, 0
	v_mov_b32_e32 v5, 0
	v_mov_b32_e32 v6, 0
	v_mov_b32_e32 v7, 0
	v_mov_b32_e32 v8, 0
	v_mov_b32_e32 v9, 0
	v_mov_b32_e32 v10, 0
	v_mov_b32_e32 v11, 0
	v_mov_b32_e32 v12, 0
	v_mov_b32_e32 v13, 0
	v_mov_b32_e32 v14, 0
	v_mov_b32_e32 v15, 0
	v_mov_b32_e32 v16, 0
	v_mov_b32_e32 v17, 0
	v_mfma_f32_32x32x16_bf16 v[18:33], v[2:5], v[2:5], 0
	v_mfma_f32_32x32x16_bf16 v[34:49], v[2:5], v[2:5], 0
	v_mfma_f32_32x32x16_bf16 v[50:65], v[2:5], v[2:5], 0
	v_mfma_f32_32x32x16_bf16 v[66:81], v[2:5], v[2:5], 0
	v_mfma_f32_32x32x16_bf16 v[82:97], v[2:5], v[2:5], 0
	v_mfma_f32_32x32x16_bf16 v[98:113], v[2:5], v[2:5], 0
	v_mfma_f32_32x32x16_bf16 v[114:129], v[2:5], v[2:5], 0
	s_andn2_b64 vcc, exec, s[18:19]
	s_nop 15
	s_nop 3
	s_cbranch_vccnz .LBB0_430
	s_add_u32 s0, s28, 0x80
	s_addc_u32 s1, s29, 0
	s_add_u32 s28, s26, 0x100
	s_addc_u32 s29, s27, 0
	s_mov_b32 s26, 0
	s_mov_b64 s[64:65], 0x80

.LBB0_452:
	v_mov_b32_e32 v2, 0
	v_mov_b32_e32 v3, 0
	v_mov_b32_e32 v4, 0
	v_mov_b32_e32 v5, 0
	v_mov_b32_e32 v6, 0
	v_mov_b32_e32 v7, 0
	v_mov_b32_e32 v8, 0
	v_mov_b32_e32 v9, 0
	v_mov_b32_e32 v10, 0
	v_mov_b32_e32 v11, 0
	v_mov_b32_e32 v12, 0
	v_mov_b32_e32 v13, 0
	v_mov_b32_e32 v14, 0
	v_mov_b32_e32 v15, 0
	v_mov_b32_e32 v16, 0
	v_mov_b32_e32 v17, 0
	v_mfma_f32_32x32x16_bf16 v[18:33], v[2:5], v[2:5], 0
	v_mfma_f32_32x32x16_bf16 v[34:49], v[2:5], v[2:5], 0
	v_mfma_f32_32x32x16_bf16 v[50:65], v[2:5], v[2:5], 0
	v_mfma_f32_32x32x16_bf16 v[66:81], v[2:5], v[2:5], 0
	v_mfma_f32_32x32x16_bf16 v[82:97], v[2:5], v[2:5], 0
	v_mfma_f32_32x32x16_bf16 v[98:113], v[2:5], v[2:5], 0
	v_mfma_f32_32x32x16_bf16 v[114:129], v[2:5], v[2:5], 0
	s_andn2_b64 vcc, exec, s[12:13]
	s_nop 15
	s_nop 3
	s_cbranch_vccnz .LBB0_455
	s_add_u32 s18, s18, 0x80
	s_addc_u32 s19, s19, 0
	s_add_u32 s43, s20, 0x100
	s_addc_u32 s44, s21, 0
	s_mov_b32 s20, 0
	s_mov_b64 s[50:51], 0x80

.LBB0_609:
	v_mov_b32_e32 v2, 0
	v_mov_b32_e32 v3, 0
	v_mov_b32_e32 v4, 0
	v_mov_b32_e32 v5, 0
	v_mov_b32_e32 v6, 0
	v_mov_b32_e32 v7, 0
	v_mov_b32_e32 v8, 0
	v_mov_b32_e32 v9, 0
	v_mov_b32_e32 v10, 0
	v_mov_b32_e32 v11, 0
	v_mov_b32_e32 v12, 0
	v_mov_b32_e32 v13, 0
	v_mov_b32_e32 v14, 0
	v_mov_b32_e32 v15, 0
	v_mov_b32_e32 v16, 0
	v_mov_b32_e32 v17, 0
	v_mfma_f32_32x32x16_bf16 v[18:33], v[2:5], v[2:5], 0
	v_mfma_f32_32x32x16_bf16 v[34:49], v[2:5], v[2:5], 0
	v_mfma_f32_32x32x16_bf16 v[50:65], v[2:5], v[2:5], 0
	v_mfma_f32_32x32x16_bf16 v[66:81], v[2:5], v[2:5], 0
	v_mfma_f32_32x32x16_bf16 v[82:97], v[2:5], v[2:5], 0
	v_mfma_f32_32x32x16_bf16 v[98:113], v[2:5], v[2:5], 0
	v_mfma_f32_32x32x16_bf16 v[114:129], v[2:5], v[2:5], 0
	s_andn2_b64 vcc, exec, s[14:15]
	s_waitcnt vmcnt(0)
	s_nop 15
	s_nop 3
	s_cbranch_vccnz .LBB0_612
	s_add_u32 s20, s20, 0x80
	s_addc_u32 s21, s21, 0
	s_add_u32 s45, s22, 0x100
	s_addc_u32 s46, s23, 0
	s_mov_b32 s22, 0
	s_mov_b64 s[52:53], 0x80

.LBB0_737:
	v_mov_b32_e32 v2, 0
	v_mov_b32_e32 v3, 0
	v_mov_b32_e32 v4, 0
	v_mov_b32_e32 v5, 0
	v_mov_b32_e32 v6, 0
	v_mov_b32_e32 v7, 0
	v_mov_b32_e32 v8, 0
	v_mov_b32_e32 v9, 0
	v_mov_b32_e32 v10, 0
	v_mov_b32_e32 v11, 0
	v_mov_b32_e32 v12, 0
	v_mov_b32_e32 v13, 0
	v_mov_b32_e32 v14, 0
	v_mov_b32_e32 v15, 0
	v_mov_b32_e32 v16, 0
	v_mov_b32_e32 v17, 0
	v_mfma_f32_32x32x16_bf16 v[18:33], v[2:5], v[2:5], 0
	v_mfma_f32_32x32x16_bf16 v[34:49], v[2:5], v[2:5], 0
	v_mfma_f32_32x32x16_bf16 v[50:65], v[2:5], v[2:5], 0
	v_mfma_f32_32x32x16_bf16 v[66:81], v[2:5], v[2:5], 0
	v_mfma_f32_32x32x16_bf16 v[82:97], v[2:5], v[2:5], 0
	v_mfma_f32_32x32x16_bf16 v[98:113], v[2:5], v[2:5], 0
	v_mfma_f32_32x32x16_bf16 v[114:129], v[2:5], v[2:5], 0
	s_andn2_b64 vcc, exec, s[20:21]
	s_waitcnt vmcnt(0)
	s_nop 15
	s_nop 3
	s_cbranch_vccnz .LBB0_741
	s_add_u32 s2, s46, 0x80
	s_addc_u32 s3, s47, 0
	s_add_u32 s46, s44, 0x100
	s_addc_u32 s47, s45, 0
	s_mov_b32 s44, 0
	s_mov_b64 vcc, 0x80

.LBB0_887:
	v_mov_b32_e32 v2, 0
	v_mov_b32_e32 v3, 0
	v_mov_b32_e32 v4, 0
	v_mov_b32_e32 v5, 0
	v_mov_b32_e32 v6, 0
	v_mov_b32_e32 v7, 0
	v_mov_b32_e32 v8, 0
	v_mov_b32_e32 v9, 0
	v_mov_b32_e32 v10, 0
	v_mov_b32_e32 v11, 0
	v_mov_b32_e32 v12, 0
	v_mov_b32_e32 v13, 0
	v_mov_b32_e32 v14, 0
	v_mov_b32_e32 v15, 0
	v_mov_b32_e32 v16, 0
	v_mov_b32_e32 v17, 0
	v_mfma_f32_32x32x16_bf16 v[18:33], v[2:5], v[2:5], 0
	v_mfma_f32_32x32x16_bf16 v[34:49], v[2:5], v[2:5], 0
	v_mfma_f32_32x32x16_bf16 v[50:65], v[2:5], v[2:5], 0
	v_mfma_f32_32x32x16_bf16 v[66:81], v[2:5], v[2:5], 0
	v_mfma_f32_32x32x16_bf16 v[82:97], v[2:5], v[2:5], 0
	v_mfma_f32_32x32x16_bf16 v[98:113], v[2:5], v[2:5], 0
	v_mfma_f32_32x32x16_bf16 v[114:129], v[2:5], v[2:5], 0
	s_andn2_b64 vcc, exec, s[12:13]
	s_waitcnt vmcnt(0)
	s_nop 15
	s_nop 3
	s_cbranch_vccnz .LBB0_890
	s_add_u32 s18, s18, 0x80
	s_addc_u32 s19, s19, 0
	s_add_u32 s43, s20, 0x100
	s_addc_u32 s44, s21, 0
	s_mov_b32 s20, 0
	s_mov_b64 s[50:51], 0x80
